# GEMM2 partial-image publish: sc1 write-through bf16 partial stores + vmcnt drain + flag, no per-unit L2 writeback fence
# speedup vs baseline: 1.0221x; 1.0182x over previous
.LBB0_613:
	s_and_b64 vcc, exec, s[0:1]
	s_cbranch_vccz .LBB0_630
	s_add_i32 s0, s15, s24
	s_ashr_i32 s1, s0, 31
	s_lshl_b64 s[0:1], s[0:1], 17
	s_add_u32 s0, s22, s0
	s_addc_u32 s1, s23, s1
	v_readlane_b32 s24, v254, 24
	s_add_u32 s24, s0, 0x823e000
	v_readlane_b32 s25, v254, 25
	v_readlane_b32 s26, v254, 26
	v_readlane_b32 s27, v254, 27
	s_addc_u32 s0, s1, 0
	s_and_b32 s25, s0, 0xffff
	s_mov_b32 s27, s26
	v_lshlrev_b32_e32 v4, 3, v249
	v_cvt_pk_bf16_f32 v2, v126, v127
	v_cvt_pk_bf16_f32 v3, v128, v129
	buffer_store_dwordx2 v[2:3], v4, s[24:27], 0 offen sc1
	v_cvt_pk_bf16_f32 v2, v122, v123
	v_cvt_pk_bf16_f32 v3, v124, v125
	s_movk_i32 s0, 0x1000
	buffer_store_dwordx2 v[2:3], v4, s[24:27], s0 offen sc1
	v_cvt_pk_bf16_f32 v2, v114, v115
	v_cvt_pk_bf16_f32 v3, v116, v117
	buffer_store_dwordx2 v[2:3], v4, s[24:27], s81 offen sc1
	v_cvt_pk_bf16_f32 v2, v106, v107
	v_cvt_pk_bf16_f32 v3, v108, v109
	buffer_store_dwordx2 v[2:3], v4, s[24:27], s93 offen sc1
	v_cvt_pk_bf16_f32 v2, v98, v99
	v_cvt_pk_bf16_f32 v3, v100, v101
	buffer_store_dwordx2 v[2:3], v4, s[24:27], s89 offen sc1
	v_cvt_pk_bf16_f32 v2, v90, v91
	v_cvt_pk_bf16_f32 v3, v92, v93
	s_movk_i32 s0, 0x5000
	buffer_store_dwordx2 v[2:3], v4, s[24:27], s0 offen sc1
	v_cvt_pk_bf16_f32 v2, v82, v83
	v_cvt_pk_bf16_f32 v3, v84, v85
	buffer_store_dwordx2 v[2:3], v4, s[24:27], s92 offen sc1
	v_cvt_pk_bf16_f32 v2, v74, v75
	v_cvt_pk_bf16_f32 v3, v76, v77
	s_movk_i32 s0, 0x7000
	buffer_store_dwordx2 v[2:3], v4, s[24:27], s0 offen sc1
	v_cvt_pk_bf16_f32 v2, v118, v119
	v_cvt_pk_bf16_f32 v3, v120, v121
	buffer_store_dwordx2 v[2:3], v4, s[24:27], s96 offen sc1
	v_cvt_pk_bf16_f32 v2, v110, v111
	v_cvt_pk_bf16_f32 v3, v112, v113
	s_mov_b32 s0, 0x9000
	buffer_store_dwordx2 v[2:3], v4, s[24:27], s0 offen sc1
	v_cvt_pk_bf16_f32 v2, v102, v103
	v_cvt_pk_bf16_f32 v3, v104, v105
	buffer_store_dwordx2 v[2:3], v4, s[24:27], s97 offen sc1
	v_cvt_pk_bf16_f32 v2, v94, v95
	v_cvt_pk_bf16_f32 v3, v96, v97
	s_mov_b32 s0, 0xb000
	buffer_store_dwordx2 v[2:3], v4, s[24:27], s0 offen sc1
	v_cvt_pk_bf16_f32 v2, v86, v87
	v_cvt_pk_bf16_f32 v3, v88, v89
	s_mov_b32 s0, 0xc000
	buffer_store_dwordx2 v[2:3], v4, s[24:27], s0 offen sc1
	v_cvt_pk_bf16_f32 v2, v78, v79
	v_cvt_pk_bf16_f32 v3, v80, v81
	s_mov_b32 s0, 0xd000
	buffer_store_dwordx2 v[2:3], v4, s[24:27], s0 offen sc1
	v_cvt_pk_bf16_f32 v2, v70, v71
	v_cvt_pk_bf16_f32 v3, v72, v73
	s_mov_b32 s0, 0xe000
	buffer_store_dwordx2 v[2:3], v4, s[24:27], s0 offen sc1
	v_cvt_pk_bf16_f32 v2, v66, v67
	v_cvt_pk_bf16_f32 v3, v68, v69
	s_mov_b32 s0, 0xf000
	buffer_store_dwordx2 v[2:3], v4, s[24:27], s0 offen sc1
	v_cvt_pk_bf16_f32 v2, v62, v63
	v_cvt_pk_bf16_f32 v3, v64, v65
	buffer_store_dwordx2 v[2:3], v4, s[24:27], s70 offen sc1
	v_cvt_pk_bf16_f32 v2, v58, v59
	v_cvt_pk_bf16_f32 v3, v60, v61
	s_mov_b32 s0, 0x11000
	buffer_store_dwordx2 v[2:3], v4, s[24:27], s0 offen sc1
	v_cvt_pk_bf16_f32 v2, v50, v51
	v_cvt_pk_bf16_f32 v3, v52, v53
	buffer_store_dwordx2 v[2:3], v4, s[24:27], s84 offen sc1
	v_cvt_pk_bf16_f32 v2, v42, v43
	v_cvt_pk_bf16_f32 v3, v44, v45
	s_mov_b32 s0, 0x13000
	buffer_store_dwordx2 v[2:3], v4, s[24:27], s0 offen sc1
	v_cvt_pk_bf16_f32 v2, v34, v35
	v_cvt_pk_bf16_f32 v3, v36, v37
	buffer_store_dwordx2 v[2:3], v4, s[24:27], s85 offen sc1
	v_cvt_pk_bf16_f32 v2, v26, v27
	v_cvt_pk_bf16_f32 v3, v28, v29
	s_mov_b32 s0, 0x15000
	buffer_store_dwordx2 v[2:3], v4, s[24:27], s0 offen sc1
	v_cvt_pk_bf16_f32 v2, v18, v19
	v_cvt_pk_bf16_f32 v3, v20, v21
	buffer_store_dwordx2 v[2:3], v4, s[24:27], s88 offen sc1
	v_cvt_pk_bf16_f32 v2, v136, v137
	v_cvt_pk_bf16_f32 v3, v134, v135
	s_mov_b32 s0, 0x17000
	buffer_store_dwordx2 v[2:3], v4, s[24:27], s0 offen sc1
	v_cvt_pk_bf16_f32 v2, v54, v55
	v_cvt_pk_bf16_f32 v3, v56, v57
	buffer_store_dwordx2 v[2:3], v4, s[24:27], s94 offen sc1
	v_cvt_pk_bf16_f32 v2, v46, v47
	v_cvt_pk_bf16_f32 v3, v48, v49
	s_mov_b32 s0, 0x19000
	buffer_store_dwordx2 v[2:3], v4, s[24:27], s0 offen sc1
	v_cvt_pk_bf16_f32 v2, v38, v39
	v_cvt_pk_bf16_f32 v3, v40, v41
	buffer_store_dwordx2 v[2:3], v4, s[24:27], s95 offen sc1
	v_cvt_pk_bf16_f32 v2, v30, v31
	v_cvt_pk_bf16_f32 v3, v32, v33
	s_mov_b32 s0, 0x1b000
	buffer_store_dwordx2 v[2:3], v4, s[24:27], s0 offen sc1
	v_cvt_pk_bf16_f32 v2, v22, v23
	v_cvt_pk_bf16_f32 v3, v24, v25
	buffer_store_dwordx2 v[2:3], v4, s[24:27], s69 offen sc1
	v_cvt_pk_bf16_f32 v2, v14, v15
	v_cvt_pk_bf16_f32 v3, v16, v17
	s_mov_b32 s0, 0x1d000
	buffer_store_dwordx2 v[2:3], v4, s[24:27], s0 offen sc1
	v_cvt_pk_bf16_f32 v2, v6, v7
	v_cvt_pk_bf16_f32 v3, v8, v9
	buffer_store_dwordx2 v[2:3], v4, s[24:27], s68 offen sc1
	v_cvt_pk_bf16_f32 v2, v12, v13
	v_cvt_pk_bf16_f32 v3, v10, v11
	s_mov_b32 s0, 0x1f000
	s_mov_b32 s22, s26
	v_writelane_b32 v254, s20, 24
	buffer_store_dwordx2 v[2:3], v4, s[24:27], s0 offen sc1
	s_waitcnt vmcnt(0)
	s_barrier
	v_writelane_b32 v254, s21, 25
	v_writelane_b32 v254, s22, 26
	v_writelane_b32 v254, s23, 27
	s_and_saveexec_b64 s[0:1], s[4:5]
	s_cbranch_execz .LBB0_616
	s_waitcnt vmcnt(0) lgkmcnt(0)
	s_waitcnt vmcnt(0)
	v_mov_b64_e32 v[2:3], s[20:21]
	flat_atomic_add v[2:3], v237 offset:4
